# S5 mode-1 items fully dynamic: each wave's first item static, the rest claimed from a per-partition atomic counter with the fetch issued one item ahead
# speedup vs baseline: 1.0102x; 1.0102x over previous
.LBB0_637:
	v_readlane_b32 s0, v253, 0
	v_readlane_b32 s1, v253, 1
	v_readlane_b32 s2, v253, 2
	v_readlane_b32 s3, v253, 3
	v_mov_b32_e32 v0, v170
	s_mov_b64 s[0:1], s[2:3]
	s_and_b64 s[0:1], s[78:79], exec
	v_ashrrev_i32_e32 v0, 6, v0
	s_movk_i32 s0, 0x84
	s_cselect_b32 s16, 0x80, s0
	v_add_u32_e32 v1, s71, v0
	s_lshr_b32 s29, s71, 3
	s_and_b32 s29, s29, 7
	s_lshr_b32 s28, s71, 6
	s_lshl_b32 s28, s28, 6
	s_add_i32 s28, s28, s29
	v_lshl_add_u32 v105, v0, 3, s28
	s_lshl_b32 s17, s16, 6
	v_cmp_gt_i32_e32 vcc, s17, v105
	s_and_saveexec_b64 s[0:1], vcc
	s_cbranch_execz .LBB0_654
	v_cvt_f32_u32_e32 v1, s16
	s_movk_i32 s2, 0x4a00
	v_mul_lo_u32 v0, v0, s2
	v_readlane_b32 s2, v255, 39
	v_rcp_iflag_f32_e32 v1, v1
	s_lshl_b32 s18, s2, 6
	s_lshl_b32 s19, s2, 9
	s_sub_i32 s2, 0, s16
	v_mul_f32_e32 v1, 0x4f7ffffe, v1
	v_cvt_u32_f32_e32 v1, v1
	v_add_u32_e32 v194, 0, v0
	s_mov_b64 s[6:7], 0
	v_mul_lo_u32 v0, s2, v1
	v_mul_hi_u32 v0, v1, v0
	v_add_u32_e32 v195, v1, v0
	v_readlane_b32 s24, v253, 2
	v_readlane_b32 s25, v253, 3
	v_readlane_b32 s28, v255, 39
	s_lshr_b32 s29, s71, 3
	s_and_b32 s29, s29, 7
	s_lshl_b32 s28, s28, 3
	s_add_i32 s28, s28, s29
	s_lshr_b32 s26, s28, 1
	s_lshl_b32 s26, s26, 8
	s_and_b32 s27, s28, 1
	s_lshl_b32 s27, s27, 7
	s_add_i32 s26, s26, s27
	s_add_i32 s26, s26, 0xc0040
	s_add_u32 s24, s24, s26
	s_addc_u32 s25, s25, 0
	s_branch .LBB0_640
.LBB0_639:
	s_or_b64 exec, exec, s[2:3]
	s_waitcnt vmcnt(0)
	v_readfirstlane_b32 s28, v184
	s_add_i32 s28, s28, 0x100
	s_lshl_b32 s28, s28, 3
	s_add_i32 s28, s28, s29
	s_cmp_ge_u32 s28, s17
	s_cbranch_scc1 .LBB0_654
	v_mov_b32_e32 v105, s28
.LBB0_640:
	s_mov_b64 s[26:27], exec
	s_mov_b64 exec, 1
	v_mov_b32_e32 v184, 1
	v_mov_b32_e32 v185, 0
	global_atomic_add v184, v185, v184, s[24:25] sc0
	s_mov_b64 exec, s[26:27]
	v_sub_u32_e32 v1, 0, v105
	v_max_i32_e32 v1, v105, v1
	v_mul_hi_u32 v2, v1, v195
	v_mul_lo_u32 v3, v2, s16
	v_sub_u32_e32 v1, v1, v3
	v_add_u32_e32 v3, 1, v2
	v_cmp_le_u32_e32 vcc, s16, v1
	v_ashrrev_i32_e32 v0, 31, v105
	v_readlane_b32 s8, v253, 0
	v_cndmask_b32_e32 v2, v2, v3, vcc
	v_subrev_u32_e32 v3, s16, v1
	v_cndmask_b32_e32 v1, v1, v3, vcc
	v_add_u32_e32 v3, 1, v2
	v_cmp_le_u32_e32 vcc, s16, v1
	v_readlane_b32 s9, v253, 1
	v_readlane_b32 s10, v253, 2
	v_cndmask_b32_e32 v1, v2, v3, vcc
	v_xor_b32_e32 v1, v1, v0
	v_sub_u32_e32 v197, v1, v0
	v_mul_lo_u32 v0, v197, s16
	v_sub_u32_e32 v4, v105, v0
	v_lshrrev_b32_e32 v0, 5, v197
	v_readlane_b32 s11, v253, 3
	s_movk_i32 s2, 0x2100
	v_mov_b32_e32 v6, v170
	s_mov_b64 s[8:9], s[10:11]
	v_mul_lo_u32 v0, v0, s2
	v_and_b32_e32 v5, 31, v197
	v_lshl_add_u32 v2, v4, 6, v0
	v_mov_b64_e32 v[0:1], s[8:9]
	v_and_b32_e32 v104, 31, v6
	v_mad_i64_i32 v[0:1], s[2:3], v2, s97, v[0:1]
	v_lshlrev_b32_e32 v112, 5, v5
	v_lshl_add_u64 v[0:1], v[0:1], 0, v[112:113]
	s_mov_b64 s[2:3], 0x7c00000
	v_mul_u32_u24_e32 v2, 0x1c00, v104
	v_bfe_u32 v196, v6, 5, 1
	v_lshl_add_u64 v[106:107], v[0:1], 0, s[2:3]
	v_lshlrev_b32_e32 v2, 1, v2
	v_mov_b32_e32 v3, v113
	v_mad_u64_u32 v[0:1], s[2:3], v104, s97, v[106:107]
	v_lshlrev_b32_e32 v112, 4, v196
	v_lshl_add_u64 v[2:3], v[106:107], 0, v[2:3]
	v_lshl_add_u64 v[2:3], v[2:3], 0, v[112:113]
	s_mov_b32 s2, 0x70000
	v_lshl_add_u64 v[0:1], v[0:1], 0, v[112:113]
	v_add_co_u32_e32 v2, vcc, s2, v2
	v_and_b32_e32 v6, 63, v6
	s_nop 0
	v_addc_co_u32_e32 v3, vcc, 0, v3, vcc
	global_load_dwordx4 v[48:51], v[0:1], off
	global_load_dwordx4 v[52:55], v[2:3], off
	v_lshlrev_b32_e32 v0, 4, v6
	v_mov_b32_e32 v1, v113
	v_lshl_add_u64 v[0:1], s[8:9], 0, v[0:1]
	s_mov_b64 s[10:11], 0x80000
	v_lshl_add_u64 v[108:109], v[0:1], 0, s[10:11]
	v_lshlrev_b32_e32 v0, 5, v104
	v_mov_b32_e32 v1, v113
	v_lshl_add_u64 v[0:1], s[8:9], 0, v[0:1]
	v_lshl_add_u64 v[0:1], v[0:1], 0, v[112:113]
	s_mov_b64 s[10:11], 0x100000
	v_lshl_add_u64 v[110:111], v[0:1], 0, s[10:11]
	v_lshlrev_b32_e32 v0, 8, v104
	v_mov_b32_e32 v1, v113
	v_lshl_add_u64 v[0:1], s[8:9], 0, v[0:1]
	v_lshl_add_u64 v[0:1], v[0:1], 0, v[112:113]
	s_mov_b64 s[10:11], 0x200000
	s_movk_i32 s5, 0x50
	v_lshl_add_u64 v[114:115], v[0:1], 0, s[10:11]
	v_lshlrev_b32_e32 v0, 2, v6
	v_mov_b32_e32 v1, v113
	v_mad_u32_u24 v199, v6, s5, v194
	s_movk_i32 s5, 0x110
	s_movk_i32 s2, 0x80
	v_lshl_add_u64 v[2:3], s[8:9], 0, v[0:1]
	s_mov_b64 s[8:9], 0x19e00000
	v_lshl_add_u32 v16, v196, 3, v194
	v_mad_u32_u24 v17, v104, s5, v194
	v_mul_u32_u24_e32 v18, 0x50, v104
	v_mov_b32_e32 v14, v113
	v_mov_b32_e32 v15, v113
	v_lshlrev_b32_e32 v198, 4, v5
	v_cmp_gt_i32_e64 s[2:3], s2, v4
	v_lshl_add_u64 v[116:117], v[2:3], 0, s[8:9]
	v_add_u32_e32 v200, v194, v0
	v_sub_u32_e32 v201, 0x83, v4
	v_add_u32_e32 v202, 0xffffff80, v4
	v_add_u32_e32 v203, 4, v4
	v_or_b32_e32 v204, s18, v5
	v_mov_b32_e32 v0, v113
	v_mov_b32_e32 v2, v113
	v_mov_b32_e32 v3, v113
	v_mov_b32_e32 v4, v113
	v_mov_b32_e32 v5, v113
	v_mov_b32_e32 v6, v113
	v_mov_b32_e32 v7, v113
	v_mov_b32_e32 v8, v113
	v_mov_b32_e32 v9, v113
	v_mov_b32_e32 v10, v113
	v_mov_b32_e32 v11, v113
	v_mov_b32_e32 v12, v113
	v_mov_b32_e32 v13, v113
	v_add_u32_e32 v205, v16, v18
	v_add_u32_e32 v206, v17, v112
	v_mov_b64_e32 v[30:31], v[14:15]
	s_mov_b32 s4, 0
	s_mov_b64 s[8:9], -1
	v_mov_b64_e32 v[28:29], v[12:13]
	v_mov_b64_e32 v[26:27], v[10:11]
	v_mov_b64_e32 v[24:25], v[8:9]
	v_mov_b64_e32 v[22:23], v[6:7]
	v_mov_b64_e32 v[20:21], v[4:5]
	v_mov_b64_e32 v[18:19], v[2:3]
	v_mov_b64_e32 v[16:17], v[0:1]
	s_branch .LBB0_642
